# selection rank loop software-pipelined (next step LDS reads issued before the compares)
# speedup vs baseline: 1.0163x; 1.0000x over previous
; DEV void attn_item(LAS unsigned char* lds, const bf16_t* P, const bf16_t* QB, const bf16_t* KV, const bf16_t* KC, const bf16_t* VC, const float* rel_bias, bf16_t* OB, int b, int g, int qt) {
;     ...
;         for (int it = 0; it < 4; ++it) { const int e = it * 512 + tid, q = e >> 5, j = e & 31;
;             float v = IA[q * 32 + j] + IA[(64 + q) * 32 + j]; if (j > 0) v += IB[q * 32 + j - 1] + IB[(64 + q) * 32 + j - 1];
;             IMPF[e] = v; }
;         __syncthreads();
;         const int cur = qt;
;         const unsigned forced = 1u | (1u << cur) | (cur > 0 ? (1u << (cur - 1)) : 0u);
;         const int need = 8 - __popc(forced);
;         for (int it = 0; it < 4; ++it) { const int q = wave * 8 + it * 2 + (lane >> 5), j = lane & 31;
;             const float v = IMPF[q * 32 + j]; int rank = 0;
;             for (int jp = 1; jp <= cur - 2; ++jp) { const float vp = IMPF[q * 32 + jp]; rank += (vp > v || (vp == v && jp < j)) ? 1 : 0; }
;             const bool sel = (j >= 1) && (j <= cur - 2) && (rank < need);
.LBB0_219:
	s_or_b64 exec, exec, s[4:5]
	s_sub_i32 s64, 30, s17
	v_lshrrev_b32_e32 v63, 5, v152
	s_sub_i32 s36, 29, s17
	v_lshl_or_b32 v66, v146, 3, v63
	s_cmp_gt_u32 s15, 2
	ds_write_b32 v62, v7 offset:6144
	s_cselect_b64 s[6:7], -1, 0
	s_cmp_lt_u32 s15, 3
	v_lshlrev_b32_e32 v64, 7, v66
	v_mov_b32_e32 v7, 0
	v_lshlrev_b32_e32 v65, 2, v60
	s_waitcnt lgkmcnt(0)
	s_barrier
	s_cbranch_scc1 .Lrk_none
	s_mov_b32 s4, 0x11d00
	v_add3_u32 v61, s4, v64, v65
	ds_read_b32 v70, v61
	ds_read_b32 v71, v61 offset:256
	ds_read_b32 v72, v61 offset:512
	ds_read_b32 v73, v61 offset:768
	v_add_u32_e32 v62, s4, v64
	v_mov_b32_e32 v74, 0
	v_mov_b32_e32 v75, 0
	v_mov_b32_e32 v76, 0
	v_mov_b32_e32 v77, 0
	s_mov_b32 s5, 1
	ds_read_b32 v78, v62 offset:4
	ds_read_b32 v79, v62 offset:260
	ds_read_b32 v80, v62 offset:516
	ds_read_b32 v81, v62 offset:772
.Lrk_loop:
	v_cmp_lt_u32_e64 s[42:43], s5, v60
	v_add_u32_e32 v62, 4, v62
	s_waitcnt lgkmcnt(0)
	v_mov_b32_e32 v86, v78
	v_mov_b32_e32 v87, v79
	v_mov_b32_e32 v88, v80
	v_mov_b32_e32 v89, v81
	ds_read_b32 v78, v62 offset:4
	ds_read_b32 v79, v62 offset:260
	ds_read_b32 v80, v62 offset:516
	ds_read_b32 v81, v62 offset:772
	v_cmp_gt_f32_e64 s[44:45], v86, v70
	v_cmp_eq_f32_e64 s[46:47], v86, v70
	v_cmp_gt_f32_e64 s[48:49], v87, v71
	v_cmp_eq_f32_e64 s[50:51], v87, v71
	v_cmp_gt_f32_e64 s[52:53], v88, v72
	v_cmp_eq_f32_e64 s[54:55], v88, v72
	v_cmp_gt_f32_e64 s[92:93], v89, v73
	v_cmp_eq_f32_e64 s[94:95], v89, v73
	s_and_b64 s[46:47], s[46:47], s[42:43]
	s_and_b64 s[50:51], s[50:51], s[42:43]
	s_and_b64 s[54:55], s[54:55], s[42:43]
	s_and_b64 s[94:95], s[94:95], s[42:43]
	s_or_b64 s[44:45], s[44:45], s[46:47]
	s_or_b64 s[48:49], s[48:49], s[50:51]
	s_or_b64 s[52:53], s[52:53], s[54:55]
	s_or_b64 s[92:93], s[92:93], s[94:95]
	s_add_i32 s5, s5, 1
	v_addc_co_u32_e64 v74, s[44:45], 0, v74, s[44:45]
	v_addc_co_u32_e64 v75, s[48:49], 0, v75, s[48:49]
	v_addc_co_u32_e64 v76, s[52:53], 0, v76, s[52:53]
	v_addc_co_u32_e64 v77, s[92:93], 0, v77, s[92:93]
	s_cmp_le_u32 s5, s36
	s_cbranch_scc1 .Lrk_loop
	s_waitcnt lgkmcnt(0)
	s_branch .Lrk_done
